# P7 main loop: static prio waves 4-7 plus the 16 priority flips and 4 redundant post-barrier lgkmcnt(0) removed outright from the MFMA segments
# speedup vs baseline: 1.0052x; 1.0052x over previous
; #define PG8_STAGE(bufoff, gbase, voff) do { _Pragma("unroll") for (int _i = 0; _i < 2; ++_i) \
;         __builtin_amdgcn_global_load_lds((const unsigned*)((const char*)(gbase) + (voff)[_i]), (PG8_LAS unsigned*)(lds + (bufoff) + ldsw + _i * 8192), 16, 0, 0); } while (0)
; #define PG8_LDA(dst, b, h) do { _Pragma("unroll") for (int m = 0; m < 4; ++m) _Pragma("unroll") for (int k = 0; k < 2; ++k) dst[m][k] = *(const PG8_LAS bf16x8*)(lds + PG8_SA(b, h) + aoff + m * 2048 + k * 1024); } while (0)
; #define PG8_LDB(dst, b, h) do { _Pragma("unroll") for (int n = 0; n < 2; ++n) _Pragma("unroll") for (int k = 0; k < 2; ++k) dst[n][k] = *(const PG8_LAS bf16x8*)(lds + PG8_SB(b, h) + boff + n * 2048 + k * 1024); } while (0)
; #define PG8_MMA(ai, bj, At, Bt) do { __builtin_amdgcn_s_setprio(1); _Pragma("unroll") for (int m = 0; m < 4; ++m) _Pragma("unroll") for (int n = 0; n < 2; ++n) _Pragma("unroll") for (int k = 0; k < 2; ++k) \
;         acc[ai][bj][m][n] = __builtin_amdgcn_mfma_f32_16x16x32_bf16(Bt[n][k], At[m][k], acc[ai][bj][m][n], 0, 0, 0); __builtin_amdgcn_s_setprio(0); } while (0)
; #define PG8_WAIT_V(n) asm volatile("s_waitcnt vmcnt(" #n ")" ::: "memory")
; #define PG8_WAIT_L(n) asm volatile("s_waitcnt lgkmcnt(" #n ")" ::: "memory")
; #define PG8_BAR __builtin_amdgcn_s_barrier()
; #define PG8_SCHED __builtin_amdgcn_sched_barrier(0)
; template <class Epi, class Sched, bool ALIGN_EPI = false, bool SP2 = false>
; __device__ __forceinline__ void gemm_phase(PG8_LAS unsigned char* lds, const Gemm g, const Sched& S, const Epi& E) {
;     ...
;             const char* a2 = last ? nA : cA + (size_t)(t + 2) * kstep; const char* b2 = last ? nB : cB + (size_t)(t + 2) * kstep;
;             const char* a3 = a2 + kstep; const char* b3 = b2 + kstep;
;             if (last && has_next) S.a_ready(nxt);
;             if constexpr (SP2) {
;             PG8_LDB(B0, 0, 0); PG8_LDB(B1, 0, 1); PG8_SCHED; PG8_LDA(At, 0, 0); PG8_STAGE(PG8_SA(1, 1), a1 + hstep, voffA);
;             PG8_WAIT_V(8); PG8_WAIT_L(0); PG8_BAR; PG8_MMA(0, 0, At, B0); PG8_MMA(0, 1, At, B1); PG8_BAR; PG8_SCHED;
;             PG8_LDA(At, 0, 1); PG8_STAGE(PG8_SB(0, 0), b2, voffB); PG8_STAGE(PG8_SB(0, 1), b2 + hstep, voffB); PG8_STAGE(PG8_SA(0, 0), a2, voffA);
.Lmy_p7_prio_done:
.LBB0_1487:
	s_add_u32 s2, s48, 0xfff80080
	s_addc_u32 s3, s49, -1
	s_add_i32 s58, 0, 0x10000
	s_cmp_eq_u32 s57, 28
	s_cselect_b32 s51, s21, s3
	s_cselect_b32 s50, s24, s2
	s_cselect_b32 s23, s19, s56
	s_cselect_b32 s22, s25, s55
	s_add_i32 s59, 0, 0x14000
	v_add_u32_e32 v156, s58, v149
	v_add_u32_e32 v172, s59, v149
	ds_read_b128 v[140:143], v156
	ds_read_b128 v[144:147], v156 offset:1024
	ds_read_b128 v[152:155], v156 offset:2048
	ds_read_b128 v[156:159], v156 offset:3072
	ds_read_b128 v[160:163], v172
	ds_read_b128 v[164:167], v172 offset:1024
	ds_read_b128 v[168:171], v172 offset:2048
	ds_read_b128 v[172:175], v172 offset:3072
	v_lshl_add_u64 v[184:185], s[48:49], 0, v[138:139]
	s_add_i32 m0, s35, 0xc000
	ds_read_b128 v[176:179], v151
	ds_read_b128 v[180:183], v151 offset:1024
	ds_read_b128 v[200:203], v151 offset:2048
	ds_read_b128 v[204:207], v151 offset:3072
	ds_read_b128 v[208:211], v151 offset:4096
	ds_read_b128 v[212:215], v151 offset:5120
	ds_read_b128 v[216:219], v151 offset:6144
	ds_read_b128 v[232:235], v151 offset:7168
	global_load_lds_dwordx4 v[184:185], off
	v_lshl_add_u64 v[184:185], s[48:49], 0, v[136:137]
	s_add_i32 m0, s35, 0xe000
	s_nop 0
	global_load_lds_dwordx4 v[184:185], off
	s_waitcnt vmcnt(8)
	s_waitcnt lgkmcnt(0)
	s_barrier
	v_mfma_f32_16x16x32_bf16 v[126:129], v[140:143], v[176:179], v[126:129]
	v_mfma_f32_16x16x32_bf16 v[118:121], v[152:155], v[176:179], v[118:121]
	v_mfma_f32_16x16x32_bf16 v[110:113], v[140:143], v[200:203], v[110:113]
	v_mfma_f32_16x16x32_bf16 v[102:105], v[152:155], v[200:203], v[102:105]
	v_mfma_f32_16x16x32_bf16 v[94:97], v[140:143], v[208:211], v[94:97]
	v_mfma_f32_16x16x32_bf16 v[86:89], v[152:155], v[208:211], v[86:89]
	v_mfma_f32_16x16x32_bf16 v[78:81], v[140:143], v[216:219], v[78:81]
	v_mfma_f32_16x16x32_bf16 v[70:73], v[152:155], v[216:219], v[70:73]
	v_mfma_f32_16x16x32_bf16 v[126:129], v[144:147], v[180:183], v[126:129]
	v_mfma_f32_16x16x32_bf16 v[118:121], v[156:159], v[180:183], v[118:121]
	v_mfma_f32_16x16x32_bf16 v[110:113], v[144:147], v[204:207], v[110:113]
	v_mfma_f32_16x16x32_bf16 v[102:105], v[156:159], v[204:207], v[102:105]
	v_mfma_f32_16x16x32_bf16 v[94:97], v[144:147], v[212:215], v[94:97]
	v_mfma_f32_16x16x32_bf16 v[86:89], v[156:159], v[212:215], v[86:89]
	v_mfma_f32_16x16x32_bf16 v[78:81], v[144:147], v[232:235], v[78:81]
	v_mfma_f32_16x16x32_bf16 v[70:73], v[156:159], v[232:235], v[70:73]
	v_mfma_f32_16x16x32_bf16 v[122:125], v[160:163], v[176:179], v[122:125]
	v_mfma_f32_16x16x32_bf16 v[114:117], v[168:171], v[176:179], v[114:117]
	v_mfma_f32_16x16x32_bf16 v[106:109], v[160:163], v[200:203], v[106:109]
	v_mfma_f32_16x16x32_bf16 v[98:101], v[168:171], v[200:203], v[98:101]
	v_mfma_f32_16x16x32_bf16 v[90:93], v[160:163], v[208:211], v[90:93]
	v_mfma_f32_16x16x32_bf16 v[82:85], v[168:171], v[208:211], v[82:85]
	v_mfma_f32_16x16x32_bf16 v[74:77], v[160:163], v[216:219], v[74:77]
	v_mfma_f32_16x16x32_bf16 v[66:69], v[168:171], v[216:219], v[66:69]
	v_mfma_f32_16x16x32_bf16 v[122:125], v[164:167], v[180:183], v[122:125]
	v_mfma_f32_16x16x32_bf16 v[114:117], v[172:175], v[180:183], v[114:117]
	v_mfma_f32_16x16x32_bf16 v[106:109], v[164:167], v[204:207], v[106:109]
	v_mfma_f32_16x16x32_bf16 v[98:101], v[172:175], v[204:207], v[98:101]
	v_mfma_f32_16x16x32_bf16 v[90:93], v[164:167], v[212:215], v[90:93]
	v_mfma_f32_16x16x32_bf16 v[82:85], v[172:175], v[212:215], v[82:85]
	v_mfma_f32_16x16x32_bf16 v[74:77], v[164:167], v[232:235], v[74:77]
	v_mfma_f32_16x16x32_bf16 v[66:69], v[172:175], v[232:235], v[66:69]
	s_barrier
	s_add_i32 s2, s58, s28
	v_lshl_add_u64 v[184:185], s[22:23], 0, v[0:1]
	s_mov_b32 m0, s2
	ds_read_b128 v[176:179], v151 offset:16384
	ds_read_b128 v[180:183], v151 offset:17408
	ds_read_b128 v[200:203], v151 offset:18432
	ds_read_b128 v[204:207], v151 offset:19456
	ds_read_b128 v[208:211], v151 offset:20480
	ds_read_b128 v[212:215], v151 offset:21504
	ds_read_b128 v[216:219], v151 offset:22528
	ds_read_b128 v[232:235], v151 offset:23552
	global_load_lds_dwordx4 v[184:185], off
	s_add_i32 m0, s2, 0x2000
	s_add_u32 s2, s22, 0x80000
	v_lshl_add_u64 v[236:237], s[22:23], 0, v[130:131]
	s_addc_u32 s3, s23, 0
	s_add_i32 s58, s59, s28
	global_load_lds_dwordx4 v[236:237], off
	v_lshl_add_u64 v[238:239], s[2:3], 0, v[0:1]
	s_mov_b32 m0, s58
	v_lshl_add_u64 v[240:241], s[50:51], 0, v[132:133]
	global_load_lds_dwordx4 v[238:239], off
	v_lshl_add_u64 v[238:239], s[2:3], 0, v[130:131]
	s_add_i32 m0, s58, 0x2000
	s_nop 0
	global_load_lds_dwordx4 v[238:239], off
	v_lshl_add_u64 v[238:239], s[50:51], 0, v[134:135]
	s_mov_b32 m0, s35
	s_nop 0
	global_load_lds_dwordx4 v[238:239], off
	s_mov_b32 m0, s36
	s_nop 0
	global_load_lds_dwordx4 v[240:241], off
	s_waitcnt vmcnt(8)
	s_waitcnt lgkmcnt(0)
	s_barrier
; #define PG8_STAGE(bufoff, gbase, voff) do { _Pragma("unroll") for (int _i = 0; _i < 2; ++_i) \
;         __builtin_amdgcn_global_load_lds((const unsigned*)((const char*)(gbase) + (voff)[_i]), (PG8_LAS unsigned*)(lds + (bufoff) + ldsw + _i * 8192), 16, 0, 0); } while (0)
; #define PG8_LDA(dst, b, h) do { _Pragma("unroll") for (int m = 0; m < 4; ++m) _Pragma("unroll") for (int k = 0; k < 2; ++k) dst[m][k] = *(const PG8_LAS bf16x8*)(lds + PG8_SA(b, h) + aoff + m * 2048 + k * 1024); } while (0)
; #define PG8_LDB(dst, b, h) do { _Pragma("unroll") for (int n = 0; n < 2; ++n) _Pragma("unroll") for (int k = 0; k < 2; ++k) dst[n][k] = *(const PG8_LAS bf16x8*)(lds + PG8_SB(b, h) + boff + n * 2048 + k * 1024); } while (0)
; #define PG8_MMA(ai, bj, At, Bt) do { __builtin_amdgcn_s_setprio(1); _Pragma("unroll") for (int m = 0; m < 4; ++m) _Pragma("unroll") for (int n = 0; n < 2; ++n) _Pragma("unroll") for (int k = 0; k < 2; ++k) \
;         acc[ai][bj][m][n] = __builtin_amdgcn_mfma_f32_16x16x32_bf16(Bt[n][k], At[m][k], acc[ai][bj][m][n], 0, 0, 0); __builtin_amdgcn_s_setprio(0); } while (0)
; #define PG8_WAIT_V(n) asm volatile("s_waitcnt vmcnt(" #n ")" ::: "memory")
; #define PG8_WAIT_L(n) asm volatile("s_waitcnt lgkmcnt(" #n ")" ::: "memory")
; #define PG8_BAR __builtin_amdgcn_s_barrier()
; #define PG8_SCHED __builtin_amdgcn_sched_barrier(0)
; template <class Epi, class Sched, bool ALIGN_EPI = false, bool SP2 = false>
; __device__ __forceinline__ void gemm_phase(PG8_LAS unsigned char* lds, const Gemm g, const Sched& S, const Epi& E) {
;     ...
;             PG8_WAIT_V(8); PG8_WAIT_L(0); PG8_BAR; PG8_MMA(1, 0, At, B0); PG8_MMA(1, 1, At, B1); PG8_BAR; PG8_SCHED;
;             PG8_LDB(B0, 1, 0); PG8_LDB(B1, 1, 1); PG8_SCHED; PG8_LDA(At, 1, 0); PG8_STAGE(PG8_SA(0, 1), a2 + hstep, voffA);
;             PG8_WAIT_V(8); PG8_WAIT_L(0); PG8_BAR; PG8_MMA(0, 0, At, B0); PG8_MMA(0, 1, At, B1); PG8_BAR; PG8_SCHED;
	v_mfma_f32_16x16x32_bf16 v[62:65], v[140:143], v[176:179], v[62:65]
	v_mfma_f32_16x16x32_bf16 v[54:57], v[152:155], v[176:179], v[54:57]
	v_mfma_f32_16x16x32_bf16 v[46:49], v[140:143], v[200:203], v[46:49]
	v_mfma_f32_16x16x32_bf16 v[38:41], v[152:155], v[200:203], v[38:41]
	v_mfma_f32_16x16x32_bf16 v[30:33], v[140:143], v[208:211], v[30:33]
	v_mfma_f32_16x16x32_bf16 v[22:25], v[152:155], v[208:211], v[22:25]
	v_mfma_f32_16x16x32_bf16 v[14:17], v[140:143], v[216:219], v[14:17]
	v_mfma_f32_16x16x32_bf16 v[6:9], v[152:155], v[216:219], v[6:9]
	v_mfma_f32_16x16x32_bf16 v[62:65], v[144:147], v[180:183], v[62:65]
	v_mfma_f32_16x16x32_bf16 v[54:57], v[156:159], v[180:183], v[54:57]
	v_mfma_f32_16x16x32_bf16 v[46:49], v[144:147], v[204:207], v[46:49]
	v_mfma_f32_16x16x32_bf16 v[38:41], v[156:159], v[204:207], v[38:41]
	v_mfma_f32_16x16x32_bf16 v[30:33], v[144:147], v[212:215], v[30:33]
	v_mfma_f32_16x16x32_bf16 v[22:25], v[156:159], v[212:215], v[22:25]
	v_mfma_f32_16x16x32_bf16 v[14:17], v[144:147], v[232:235], v[14:17]
	v_mfma_f32_16x16x32_bf16 v[6:9], v[156:159], v[232:235], v[6:9]
	v_mfma_f32_16x16x32_bf16 v[58:61], v[160:163], v[176:179], v[58:61]
	v_mfma_f32_16x16x32_bf16 v[50:53], v[168:171], v[176:179], v[50:53]
	v_mfma_f32_16x16x32_bf16 v[42:45], v[160:163], v[200:203], v[42:45]
	v_mfma_f32_16x16x32_bf16 v[34:37], v[168:171], v[200:203], v[34:37]
	v_mfma_f32_16x16x32_bf16 v[26:29], v[160:163], v[208:211], v[26:29]
	v_mfma_f32_16x16x32_bf16 v[18:21], v[168:171], v[208:211], v[18:21]
	v_mfma_f32_16x16x32_bf16 v[10:13], v[160:163], v[216:219], v[10:13]
	v_mfma_f32_16x16x32_bf16 v[2:5], v[168:171], v[216:219], v[2:5]
	v_mfma_f32_16x16x32_bf16 v[58:61], v[164:167], v[180:183], v[58:61]
	v_mfma_f32_16x16x32_bf16 v[50:53], v[172:175], v[180:183], v[50:53]
	v_mfma_f32_16x16x32_bf16 v[42:45], v[164:167], v[204:207], v[42:45]
	v_mfma_f32_16x16x32_bf16 v[34:37], v[172:175], v[204:207], v[34:37]
	v_mfma_f32_16x16x32_bf16 v[26:29], v[164:167], v[212:215], v[26:29]
	v_mfma_f32_16x16x32_bf16 v[18:21], v[172:175], v[212:215], v[18:21]
	v_mfma_f32_16x16x32_bf16 v[10:13], v[164:167], v[232:235], v[10:13]
	v_mfma_f32_16x16x32_bf16 v[2:5], v[172:175], v[232:235], v[2:5]
	s_barrier
	s_add_i32 s58, 0, 0x18000
	s_add_i32 s59, 0, 0x1c000
	v_add_u32_e32 v156, s58, v149
	v_add_u32_e32 v172, s59, v149
	ds_read_b128 v[140:143], v156
	ds_read_b128 v[144:147], v156 offset:1024
	ds_read_b128 v[152:155], v156 offset:2048
	ds_read_b128 v[156:159], v156 offset:3072
	ds_read_b128 v[160:163], v172
	ds_read_b128 v[164:167], v172 offset:1024
	ds_read_b128 v[168:171], v172 offset:2048
	ds_read_b128 v[172:175], v172 offset:3072
	s_add_u32 s2, s50, 0x80000
	s_addc_u32 s3, s51, 0
	s_mov_b32 m0, s37
	v_lshl_add_u64 v[242:243], s[2:3], 0, v[134:135]
	ds_read_b128 v[176:179], v151 offset:32768
	ds_read_b128 v[180:183], v151 offset:33792
	ds_read_b128 v[200:203], v151 offset:34816
	ds_read_b128 v[204:207], v151 offset:35840
	ds_read_b128 v[208:211], v151 offset:36864
	ds_read_b128 v[212:215], v151 offset:37888
	ds_read_b128 v[216:219], v151 offset:38912
	ds_read_b128 v[232:235], v151 offset:39936
	global_load_lds_dwordx4 v[242:243], off
	v_lshl_add_u64 v[242:243], s[2:3], 0, v[132:133]
	s_mov_b32 m0, s38
	s_nop 0
	global_load_lds_dwordx4 v[242:243], off
	s_waitcnt vmcnt(8)
	s_waitcnt lgkmcnt(0)
	s_barrier
	v_mfma_f32_16x16x32_bf16 v[126:129], v[140:143], v[176:179], v[126:129]
	v_mfma_f32_16x16x32_bf16 v[118:121], v[152:155], v[176:179], v[118:121]
	v_mfma_f32_16x16x32_bf16 v[110:113], v[140:143], v[200:203], v[110:113]
	v_mfma_f32_16x16x32_bf16 v[102:105], v[152:155], v[200:203], v[102:105]
	v_mfma_f32_16x16x32_bf16 v[94:97], v[140:143], v[208:211], v[94:97]
	v_mfma_f32_16x16x32_bf16 v[86:89], v[152:155], v[208:211], v[86:89]
	v_mfma_f32_16x16x32_bf16 v[78:81], v[140:143], v[216:219], v[78:81]
	v_mfma_f32_16x16x32_bf16 v[70:73], v[152:155], v[216:219], v[70:73]
	v_mfma_f32_16x16x32_bf16 v[126:129], v[144:147], v[180:183], v[126:129]
	v_mfma_f32_16x16x32_bf16 v[118:121], v[156:159], v[180:183], v[118:121]
	v_mfma_f32_16x16x32_bf16 v[110:113], v[144:147], v[204:207], v[110:113]
	v_mfma_f32_16x16x32_bf16 v[102:105], v[156:159], v[204:207], v[102:105]
	v_mfma_f32_16x16x32_bf16 v[94:97], v[144:147], v[212:215], v[94:97]
	v_mfma_f32_16x16x32_bf16 v[86:89], v[156:159], v[212:215], v[86:89]
	v_mfma_f32_16x16x32_bf16 v[78:81], v[144:147], v[232:235], v[78:81]
	v_mfma_f32_16x16x32_bf16 v[70:73], v[156:159], v[232:235], v[70:73]
	v_mfma_f32_16x16x32_bf16 v[122:125], v[160:163], v[176:179], v[122:125]
	v_mfma_f32_16x16x32_bf16 v[114:117], v[168:171], v[176:179], v[114:117]
	v_mfma_f32_16x16x32_bf16 v[106:109], v[160:163], v[200:203], v[106:109]
	v_mfma_f32_16x16x32_bf16 v[98:101], v[168:171], v[200:203], v[98:101]
	v_mfma_f32_16x16x32_bf16 v[90:93], v[160:163], v[208:211], v[90:93]
	v_mfma_f32_16x16x32_bf16 v[82:85], v[168:171], v[208:211], v[82:85]
	v_mfma_f32_16x16x32_bf16 v[74:77], v[160:163], v[216:219], v[74:77]
	v_mfma_f32_16x16x32_bf16 v[66:69], v[168:171], v[216:219], v[66:69]
	v_mfma_f32_16x16x32_bf16 v[122:125], v[164:167], v[180:183], v[122:125]
	v_mfma_f32_16x16x32_bf16 v[114:117], v[172:175], v[180:183], v[114:117]
	v_mfma_f32_16x16x32_bf16 v[106:109], v[164:167], v[204:207], v[106:109]
	v_mfma_f32_16x16x32_bf16 v[98:101], v[172:175], v[204:207], v[98:101]
	v_mfma_f32_16x16x32_bf16 v[90:93], v[164:167], v[212:215], v[90:93]
	v_mfma_f32_16x16x32_bf16 v[82:85], v[172:175], v[212:215], v[82:85]
	v_mfma_f32_16x16x32_bf16 v[74:77], v[164:167], v[232:235], v[74:77]
	v_mfma_f32_16x16x32_bf16 v[66:69], v[172:175], v[232:235], v[66:69]
	s_barrier
; #define PG8_STAGE(bufoff, gbase, voff) do { _Pragma("unroll") for (int _i = 0; _i < 2; ++_i) \
;         __builtin_amdgcn_global_load_lds((const unsigned*)((const char*)(gbase) + (voff)[_i]), (PG8_LAS unsigned*)(lds + (bufoff) + ldsw + _i * 8192), 16, 0, 0); } while (0)
; #define PG8_LDA(dst, b, h) do { _Pragma("unroll") for (int m = 0; m < 4; ++m) _Pragma("unroll") for (int k = 0; k < 2; ++k) dst[m][k] = *(const PG8_LAS bf16x8*)(lds + PG8_SA(b, h) + aoff + m * 2048 + k * 1024); } while (0)
; #define PG8_MMA(ai, bj, At, Bt) do { __builtin_amdgcn_s_setprio(1); _Pragma("unroll") for (int m = 0; m < 4; ++m) _Pragma("unroll") for (int n = 0; n < 2; ++n) _Pragma("unroll") for (int k = 0; k < 2; ++k) \
;         acc[ai][bj][m][n] = __builtin_amdgcn_mfma_f32_16x16x32_bf16(Bt[n][k], At[m][k], acc[ai][bj][m][n], 0, 0, 0); __builtin_amdgcn_s_setprio(0); } while (0)
; #define PG8_WAIT_V(n) asm volatile("s_waitcnt vmcnt(" #n ")" ::: "memory")
; #define PG8_WAIT_L(n) asm volatile("s_waitcnt lgkmcnt(" #n ")" ::: "memory")
; #define PG8_BAR __builtin_amdgcn_s_barrier()
; #define PG8_SCHED __builtin_amdgcn_sched_barrier(0)
; template <class Epi, class Sched, bool ALIGN_EPI = false, bool SP2 = false>
; __device__ __forceinline__ void gemm_phase(PG8_LAS unsigned char* lds, const Gemm g, const Sched& S, const Epi& E) {
;     ...
;             PG8_LDA(At, 1, 1); PG8_STAGE(PG8_SB(1, 0), b3, voffB); PG8_STAGE(PG8_SB(1, 1), b3 + hstep, voffB); PG8_STAGE(PG8_SA(1, 0), a3, voffA);
;             PG8_WAIT_V(8); PG8_WAIT_L(0); PG8_BAR; PG8_MMA(1, 0, At, B0); PG8_MMA(1, 1, At, B1); PG8_BAR; PG8_SCHED;
;     __device__ __forceinline__ void operator()(const f32x4 (&acc)[2][2][4][2], const Unit& u, int wr, int wc, int fr, int fq) const {
;         const int row0 = u.pm * BM + wr * 64 + fr, col0 = u.pn * HALF + wc * 32 + 8 * fq;
;         float rs[2][4];
; #pragma unroll
;         for (int ai = 0; ai < 2; ++ai)
; #pragma unroll
;             for (int m = 0; m < 4; ++m) rs[ai][m] = ssq[row0 + ai * HALF + m * 16];
; #pragma unroll
;         for (int ai = 0; ai < 2; ++ai)
; #pragma unroll
;             for (int m = 0; m < 4; ++m) { bf16_t* rowp = O + (size_t)(row0 + ai * HALF + m * 16) * DFF + col0; const float rsv = rsqrtf(rs[ai][m] * (1.f / D) + EPS);
	s_add_i32 s2, s58, s28
	v_lshl_add_u64 v[184:185], v[184:185], 0, s[0:1]
	s_mov_b32 m0, s2
	ds_read_b128 v[176:179], v151 offset:49152
	ds_read_b128 v[180:183], v151 offset:50176
	ds_read_b128 v[200:203], v151 offset:51200
	ds_read_b128 v[204:207], v151 offset:52224
	ds_read_b128 v[208:211], v151 offset:53248
	ds_read_b128 v[212:215], v151 offset:54272
	ds_read_b128 v[216:219], v151 offset:55296
	ds_read_b128 v[232:235], v151 offset:56320
	global_load_lds_dwordx4 v[184:185], off
	s_add_i32 m0, s2, 0x2000
	s_add_u32 s2, s22, 0x80080
	v_lshl_add_u64 v[184:185], v[236:237], 0, s[0:1]
	s_addc_u32 s3, s23, 0
	s_add_i32 s22, s59, s28
	global_load_lds_dwordx4 v[184:185], off
	v_lshl_add_u64 v[184:185], s[2:3], 0, v[0:1]
	s_mov_b32 m0, s22
	s_nop 0
	global_load_lds_dwordx4 v[184:185], off
	v_lshl_add_u64 v[184:185], s[2:3], 0, v[130:131]
	s_add_i32 m0, s22, 0x2000
	s_nop 0
	global_load_lds_dwordx4 v[184:185], off
	v_lshl_add_u64 v[184:185], v[238:239], 0, s[0:1]
	s_mov_b32 m0, s47
	s_nop 0
	global_load_lds_dwordx4 v[184:185], off
	v_lshl_add_u64 v[184:185], v[240:241], 0, s[0:1]
	s_mov_b32 m0, s52
	s_nop 0
	global_load_lds_dwordx4 v[184:185], off
	s_waitcnt vmcnt(8)
	s_waitcnt lgkmcnt(0)
	s_barrier
	v_mfma_f32_16x16x32_bf16 v[62:65], v[140:143], v[176:179], v[62:65]
	v_mfma_f32_16x16x32_bf16 v[54:57], v[152:155], v[176:179], v[54:57]
	v_mfma_f32_16x16x32_bf16 v[46:49], v[140:143], v[200:203], v[46:49]
	v_mfma_f32_16x16x32_bf16 v[38:41], v[152:155], v[200:203], v[38:41]
	v_mfma_f32_16x16x32_bf16 v[30:33], v[140:143], v[208:211], v[30:33]
	v_mfma_f32_16x16x32_bf16 v[22:25], v[152:155], v[208:211], v[22:25]
	v_mfma_f32_16x16x32_bf16 v[14:17], v[140:143], v[216:219], v[14:17]
	v_mfma_f32_16x16x32_bf16 v[6:9], v[152:155], v[216:219], v[6:9]
	v_mfma_f32_16x16x32_bf16 v[62:65], v[144:147], v[180:183], v[62:65]
	v_mfma_f32_16x16x32_bf16 v[54:57], v[156:159], v[180:183], v[54:57]
	v_mfma_f32_16x16x32_bf16 v[46:49], v[144:147], v[204:207], v[46:49]
	v_mfma_f32_16x16x32_bf16 v[38:41], v[156:159], v[204:207], v[38:41]
	v_mfma_f32_16x16x32_bf16 v[30:33], v[144:147], v[212:215], v[30:33]
	v_mfma_f32_16x16x32_bf16 v[22:25], v[156:159], v[212:215], v[22:25]
	v_mfma_f32_16x16x32_bf16 v[14:17], v[144:147], v[232:235], v[14:17]
	v_mfma_f32_16x16x32_bf16 v[6:9], v[156:159], v[232:235], v[6:9]
	v_mfma_f32_16x16x32_bf16 v[58:61], v[160:163], v[176:179], v[58:61]
	v_mfma_f32_16x16x32_bf16 v[50:53], v[168:171], v[176:179], v[50:53]
	v_mfma_f32_16x16x32_bf16 v[42:45], v[160:163], v[200:203], v[42:45]
	v_mfma_f32_16x16x32_bf16 v[34:37], v[168:171], v[200:203], v[34:37]
	v_mfma_f32_16x16x32_bf16 v[26:29], v[160:163], v[208:211], v[26:29]
	v_mfma_f32_16x16x32_bf16 v[18:21], v[168:171], v[208:211], v[18:21]
	v_mfma_f32_16x16x32_bf16 v[10:13], v[160:163], v[216:219], v[10:13]
	v_mfma_f32_16x16x32_bf16 v[2:5], v[168:171], v[216:219], v[2:5]
	v_mfma_f32_16x16x32_bf16 v[58:61], v[164:167], v[180:183], v[58:61]
	v_mfma_f32_16x16x32_bf16 v[50:53], v[172:175], v[180:183], v[50:53]
	v_mfma_f32_16x16x32_bf16 v[42:45], v[164:167], v[204:207], v[42:45]
	v_mfma_f32_16x16x32_bf16 v[34:37], v[172:175], v[204:207], v[34:37]
	v_mfma_f32_16x16x32_bf16 v[26:29], v[164:167], v[212:215], v[26:29]
	v_mfma_f32_16x16x32_bf16 v[18:21], v[172:175], v[212:215], v[18:21]
	v_mfma_f32_16x16x32_bf16 v[10:13], v[164:167], v[232:235], v[10:13]
	v_mfma_f32_16x16x32_bf16 v[2:5], v[172:175], v[232:235], v[2:5]
	s_barrier
	s_add_i32 s57, s57, 2
	s_add_u32 s55, s55, 0x100
	s_addc_u32 s56, s56, 0
	s_add_u32 s48, s48, 0x100
	s_addc_u32 s49, s49, 0
	s_cmp_gt_u32 s57, 29
	s_cbranch_scc0 .LBB0_1487
	s_setprio 0
	s_and_b64 vcc, exec, s[16:17]
	s_cbranch_vccz .LBB0_1490
	s_barrier
.LBB0_1490:
	v_lshl_add_u32 v144, s46, 8, v148
	v_ashrrev_i32_e32 v145, 31, v144
	v_lshl_add_u64 v[140:141], v[144:145], 2, s[12:13]
	flat_load_dword v146, v[140:141]
	flat_load_dword v164, v[140:141] offset:64
	flat_load_dword v162, v[140:141] offset:128
	flat_load_dword v160, v[140:141] offset:192
	flat_load_dword v158, v[140:141] offset:512
	flat_load_dword v156, v[140:141] offset:576
	flat_load_dword v154, v[140:141] offset:640
	flat_load_dword v152, v[140:141] offset:704
	v_mov_b32_e32 v166, v126
	v_lshl_or_b32 v142, s54, 7, v150
	v_ashrrev_i32_e32 v143, 31, v142
	v_mov_b64_e32 v[140:141], s[8:9]
	v_or_b32_e32 v165, 16, v144
	v_or_b32_e32 v163, 32, v144
	v_or_b32_e32 v161, 48, v144
	v_add_u32_e32 v159, 0x80, v144
	v_add_u32_e32 v157, 0x90, v144
	v_add_u32_e32 v155, 0xa0, v144
	v_add_u32_e32 v153, 0xb0, v144
	v_mad_i64_i32 v[144:145], s[2:3], v144, s34, v[140:141]
	s_mov_b64 s[22:23], -1
	s_mov_b64 s[56:57], s[94:95]
	s_waitcnt vmcnt(0) lgkmcnt(0)
; __device__ __forceinline__ unsigned pk2(float lo, float hi) { unsigned r; asm volatile("v_cvt_pk_bf16_f32 %0, %1, %2" : "=v"(r) : "v"(lo), "v"(hi)); return r; }
;     __device__ __forceinline__ void operator()(const f32x4 (&acc)[2][2][4][2], const Unit& u, int wr, int wc, int fr, int fq) const {
;     ...
;             for (int m = 0; m < 4; ++m) { bf16_t* rowp = O + (size_t)(row0 + ai * HALF + m * 16) * DFF + col0; const float rsv = rsqrtf(rs[ai][m] * (1.f / D) + EPS);
;                 const float rs2 = rsv * rsv, nrs = -1.4426950409f * rsv;
;                 float v[8];
; #pragma unroll
;                 for (int n = 0; n < 2; ++n)
; #pragma unroll
;                     for (int j = 0; j < 4; ++j) {
;                         const float g0 = acc[ai][0][m][n][j], u0 = acc[ai][1][m][n][j];
;                         v[n * 4 + j] = (g0 * u0) * (rs2 * __builtin_amdgcn_rcpf(1.0f + __builtin_amdgcn_exp2f(g0 * nrs))); }
;                 u32x4 w; w.x = pk2(v[0], v[1]); w.y = pk2(v[2], v[3]); w.z = pk2(v[4], v[5]); w.w = pk2(v[6], v[7]);
;                 *(u32x4*)rowp = w; }
	v_fmamk_f32 v146, v146, 0x3a000000, v223
	v_cmp_gt_f32_e32 vcc, s29, v146
	v_mul_f32_e32 v147, 0x4b800000, v146
	s_nop 0
	v_cndmask_b32_e32 v146, v146, v147, vcc
	v_rsq_f32_e32 v146, v146
	s_nop 0
	v_mul_f32_e32 v147, 0x45800000, v146
	v_cndmask_b32_e32 v146, v146, v147, vcc
	v_mul_f32_e32 v168, 0xbfb8aa3b, v146
	v_mul_f32_e32 v147, v146, v146
	v_mul_f32_e32 v146, v126, v168
	v_exp_f32_e32 v146, v146
	s_nop 0
	v_add_f32_e32 v146, 1.0, v146
	v_rcp_f32_e32 v167, v146
	v_mov_b32_e32 v146, v122
	v_mul_f32_e32 v122, v127, v168
	v_exp_f32_e32 v122, v122
	v_pk_mul_f32 v[166:167], v[146:147], v[166:167]
	v_mov_b32_e32 v146, v123
	v_mul_f32_e32 v126, v166, v167
	v_add_f32_e32 v122, 1.0, v122
	v_rcp_f32_e32 v167, v122
	v_mov_b32_e32 v166, v127
	v_pk_mul_f32 v[122:123], v[146:147], v[166:167]
	s_nop 0
	v_mul_f32_e32 v127, v122, v123
	v_mul_f32_e32 v122, v128, v168
	v_exp_f32_e32 v122, v122
	v_mov_b32_e32 v146, v124
	v_add_f32_e32 v122, 1.0, v122
	v_rcp_f32_e32 v123, v122
	v_mov_b32_e32 v122, v128
	v_pk_mul_f32 v[122:123], v[146:147], v[122:123]
	s_nop 0
	v_mul_f32_e32 v124, v122, v123
	v_mul_f32_e32 v122, v129, v168
	v_exp_f32_e32 v122, v122
	v_mov_b32_e32 v146, v125
	v_add_f32_e32 v122, 1.0, v122
	v_rcp_f32_e32 v123, v122
	v_mov_b32_e32 v122, v129
	v_pk_mul_f32 v[122:123], v[146:147], v[122:123]
	s_nop 0
	v_mul_f32_e32 v125, v122, v123
	v_mul_f32_e32 v122, v118, v168
	v_exp_f32_e32 v122, v122
	v_mov_b32_e32 v146, v114
	v_mul_f32_e32 v114, v119, v168
	v_exp_f32_e32 v114, v114
	v_add_f32_e32 v122, 1.0, v122
	v_rcp_f32_e32 v123, v122
	v_mov_b32_e32 v122, v118
	v_add_f32_e32 v114, 1.0, v114
	v_pk_mul_f32 v[122:123], v[146:147], v[122:123]
	s_nop 0
	v_mul_f32_e32 v118, v122, v123
	v_rcp_f32_e32 v123, v114
	v_mov_b32_e32 v146, v115
	v_mov_b32_e32 v122, v119
	v_pk_mul_f32 v[114:115], v[146:147], v[122:123]
	s_nop 0
	v_mul_f32_e32 v119, v114, v115
	v_mul_f32_e32 v114, v120, v168
	v_exp_f32_e32 v114, v114
	v_mov_b32_e32 v146, v116
	v_cvt_pk_bf16_f32 v116, v126, v127
	v_add_f32_e32 v114, 1.0, v114
	v_rcp_f32_e32 v115, v114
	v_mov_b32_e32 v114, v120
	v_pk_mul_f32 v[114:115], v[146:147], v[114:115]
	s_nop 0
	v_mul_f32_e32 v122, v114, v115
	v_mul_f32_e32 v114, v121, v168
	v_exp_f32_e32 v114, v114
	v_mov_b32_e32 v146, v117
	v_cvt_pk_bf16_f32 v117, v124, v125
	v_cvt_pk_bf16_f32 v118, v118, v119
	v_add_f32_e32 v114, 1.0, v114
	v_rcp_f32_e32 v115, v114
	v_mov_b32_e32 v114, v121
	v_pk_mul_f32 v[114:115], v[146:147], v[114:115]
	s_nop 0
	v_mul_f32_e32 v123, v114, v115
	v_lshlrev_b64 v[114:115], 1, v[142:143]
	v_lshl_add_u64 v[120:121], v[144:145], 0, v[114:115]
	v_cvt_pk_bf16_f32 v119, v122, v123
	flat_store_dwordx4 v[120:121], v[116:119]
	v_mov_b32_e32 v120, v110
	s_nop 0
	v_fmamk_f32 v118, v164, 0x3a000000, v223
	v_cmp_gt_f32_e32 vcc, s29, v118
	v_mul_f32_e32 v119, 0x4b800000, v118
	v_mad_i64_i32 v[116:117], s[2:3], v165, s34, v[140:141]
	v_cndmask_b32_e32 v118, v118, v119, vcc
	v_rsq_f32_e32 v118, v118
	s_nop 0
	v_mul_f32_e32 v119, 0x45800000, v118
	v_cndmask_b32_e32 v118, v118, v119, vcc
	v_mul_f32_e32 v122, 0xbfb8aa3b, v118
	v_mul_f32_e32 v119, v118, v118
	v_mul_f32_e32 v118, v110, v122
	v_exp_f32_e32 v118, v118
	s_nop 0
	v_add_f32_e32 v118, 1.0, v118
	v_rcp_f32_e32 v121, v118
	v_mov_b32_e32 v118, v106
	v_mul_f32_e32 v106, v111, v122
	v_exp_f32_e32 v106, v106
	v_pk_mul_f32 v[120:121], v[118:119], v[120:121]
	v_mov_b32_e32 v118, v107
	v_mul_f32_e32 v110, v120, v121
	v_add_f32_e32 v106, 1.0, v106
	v_rcp_f32_e32 v121, v106
	v_mov_b32_e32 v120, v111
	v_pk_mul_f32 v[106:107], v[118:119], v[120:121]
	s_nop 0
	v_mul_f32_e32 v111, v106, v107
	v_mul_f32_e32 v106, v112, v122
	v_exp_f32_e32 v106, v106
	v_mov_b32_e32 v118, v108
	v_add_f32_e32 v106, 1.0, v106
	v_rcp_f32_e32 v107, v106
	v_mov_b32_e32 v106, v112
	v_pk_mul_f32 v[106:107], v[118:119], v[106:107]
	s_nop 0
	v_mul_f32_e32 v108, v106, v107
	v_mul_f32_e32 v106, v113, v122
	v_exp_f32_e32 v106, v106
	v_mov_b32_e32 v118, v109
	v_add_f32_e32 v106, 1.0, v106
	v_rcp_f32_e32 v107, v106
	v_mov_b32_e32 v106, v113
	v_pk_mul_f32 v[106:107], v[118:119], v[106:107]
	s_nop 0
	v_mul_f32_e32 v109, v106, v107
	v_mul_f32_e32 v106, v102, v122
	v_exp_f32_e32 v106, v106
	v_mov_b32_e32 v118, v98
	v_mul_f32_e32 v98, v103, v122
	v_exp_f32_e32 v98, v98
	v_add_f32_e32 v106, 1.0, v106
	v_rcp_f32_e32 v107, v106
	v_mov_b32_e32 v106, v102
	v_add_f32_e32 v98, 1.0, v98
	v_pk_mul_f32 v[106:107], v[118:119], v[106:107]
	s_nop 0
	v_mul_f32_e32 v112, v106, v107
	v_rcp_f32_e32 v107, v98
	v_mov_b32_e32 v118, v99
	v_mov_b32_e32 v106, v103
	v_lshl_add_u64 v[102:103], v[116:117], 0, v[114:115]
	v_pk_mul_f32 v[98:99], v[118:119], v[106:107]
	v_mov_b32_e32 v118, v100
	v_mul_f32_e32 v106, v98, v99
	v_mul_f32_e32 v98, v104, v122
	v_exp_f32_e32 v98, v98
	s_nop 0
	v_add_f32_e32 v98, 1.0, v98
	v_rcp_f32_e32 v99, v98
	v_mov_b32_e32 v98, v104
	v_pk_mul_f32 v[98:99], v[118:119], v[98:99]
	s_nop 0
	v_mul_f32_e32 v104, v98, v99
	v_mul_f32_e32 v98, v105, v122
	v_exp_f32_e32 v98, v98
	v_mov_b32_e32 v118, v101
	v_add_f32_e32 v98, 1.0, v98
	v_rcp_f32_e32 v99, v98
	v_mov_b32_e32 v98, v105
	v_pk_mul_f32 v[98:99], v[118:119], v[98:99]
	s_nop 0
	v_mul_f32_e32 v101, v98, v99
	v_cvt_pk_bf16_f32 v98, v110, v111
	v_cvt_pk_bf16_f32 v99, v108, v109
	v_cvt_pk_bf16_f32 v100, v112, v106
	v_cvt_pk_bf16_f32 v101, v104, v101
	flat_store_dwordx4 v[102:103], v[98:101]
	v_mov_b32_e32 v102, v94
	s_nop 0
	v_fmamk_f32 v100, v162, 0x3a000000, v223
	v_cmp_gt_f32_e32 vcc, s29, v100
	v_mul_f32_e32 v101, 0x4b800000, v100
	v_mad_i64_i32 v[98:99], s[2:3], v163, s34, v[140:141]
	v_cndmask_b32_e32 v100, v100, v101, vcc
	v_rsq_f32_e32 v100, v100
	s_nop 0
	v_mul_f32_e32 v101, 0x45800000, v100
; __device__ __forceinline__ unsigned pk2(float lo, float hi) { unsigned r; asm volatile("v_cvt_pk_bf16_f32 %0, %1, %2" : "=v"(r) : "v"(lo), "v"(hi)); return r; }
;     __device__ __forceinline__ void operator()(const f32x4 (&acc)[2][2][4][2], const Unit& u, int wr, int wc, int fr, int fq) const {
;     ...
;             for (int m = 0; m < 4; ++m) { bf16_t* rowp = O + (size_t)(row0 + ai * HALF + m * 16) * DFF + col0; const float rsv = rsqrtf(rs[ai][m] * (1.f / D) + EPS);
;                 const float rs2 = rsv * rsv, nrs = -1.4426950409f * rsv;
;                 float v[8];
; #pragma unroll
;                 for (int n = 0; n < 2; ++n)
; #pragma unroll
;                     for (int j = 0; j < 4; ++j) {
;                         const float g0 = acc[ai][0][m][n][j], u0 = acc[ai][1][m][n][j];
;                         v[n * 4 + j] = (g0 * u0) * (rs2 * __builtin_amdgcn_rcpf(1.0f + __builtin_amdgcn_exp2f(g0 * nrs))); }
;                 u32x4 w; w.x = pk2(v[0], v[1]); w.y = pk2(v[2], v[3]); w.z = pk2(v[4], v[5]); w.w = pk2(v[6], v[7]);
;                 *(u32x4*)rowp = w; }
	v_cndmask_b32_e32 v100, v100, v101, vcc
	v_mul_f32_e32 v104, 0xbfb8aa3b, v100
	v_mul_f32_e32 v101, v100, v100
	v_mul_f32_e32 v100, v94, v104
	v_exp_f32_e32 v100, v100
	s_nop 0
	v_add_f32_e32 v100, 1.0, v100
	v_rcp_f32_e32 v103, v100
	v_mov_b32_e32 v100, v90
	v_mul_f32_e32 v90, v95, v104
	v_exp_f32_e32 v90, v90
	v_pk_mul_f32 v[102:103], v[100:101], v[102:103]
	v_mov_b32_e32 v100, v91
	v_mul_f32_e32 v94, v102, v103
	v_add_f32_e32 v90, 1.0, v90
	v_rcp_f32_e32 v103, v90
	v_mov_b32_e32 v102, v95
	v_pk_mul_f32 v[90:91], v[100:101], v[102:103]
	s_nop 0
	v_mul_f32_e32 v95, v90, v91
	v_mul_f32_e32 v90, v96, v104
	v_exp_f32_e32 v90, v90
	v_mov_b32_e32 v100, v92
	v_add_f32_e32 v90, 1.0, v90
	v_rcp_f32_e32 v91, v90
	v_mov_b32_e32 v90, v96
	v_pk_mul_f32 v[90:91], v[100:101], v[90:91]
	s_nop 0
	v_mul_f32_e32 v92, v90, v91
	v_mul_f32_e32 v90, v97, v104
	v_exp_f32_e32 v90, v90
	v_mov_b32_e32 v100, v93
	v_add_f32_e32 v90, 1.0, v90
	v_rcp_f32_e32 v91, v90
	v_mov_b32_e32 v90, v97
	v_pk_mul_f32 v[90:91], v[100:101], v[90:91]
	s_nop 0
	v_mul_f32_e32 v93, v90, v91
	v_mul_f32_e32 v90, v86, v104
	v_exp_f32_e32 v90, v90
	v_mov_b32_e32 v100, v82
	v_mul_f32_e32 v82, v87, v104
	v_exp_f32_e32 v82, v82
	v_add_f32_e32 v90, 1.0, v90
	v_rcp_f32_e32 v91, v90
	v_mov_b32_e32 v90, v86
	v_add_f32_e32 v82, 1.0, v82
	v_pk_mul_f32 v[90:91], v[100:101], v[90:91]
	s_nop 0
	v_mul_f32_e32 v96, v90, v91
	v_rcp_f32_e32 v91, v82
	v_mov_b32_e32 v100, v83
	v_mov_b32_e32 v90, v87
	v_lshl_add_u64 v[86:87], v[98:99], 0, v[114:115]
	v_pk_mul_f32 v[82:83], v[100:101], v[90:91]
	v_mov_b32_e32 v100, v84
	v_mul_f32_e32 v90, v82, v83
	v_mul_f32_e32 v82, v88, v104
	v_exp_f32_e32 v82, v82
	s_nop 0
	v_add_f32_e32 v82, 1.0, v82
	v_rcp_f32_e32 v83, v82
	v_mov_b32_e32 v82, v88
	v_pk_mul_f32 v[82:83], v[100:101], v[82:83]
	s_nop 0
	v_mul_f32_e32 v88, v82, v83
	v_mul_f32_e32 v82, v89, v104
	v_exp_f32_e32 v82, v82
	v_mov_b32_e32 v100, v85
	v_add_f32_e32 v82, 1.0, v82
	v_rcp_f32_e32 v83, v82
	v_mov_b32_e32 v82, v89
	v_pk_mul_f32 v[82:83], v[100:101], v[82:83]
	s_nop 0
	v_mul_f32_e32 v85, v82, v83
	v_cvt_pk_bf16_f32 v82, v94, v95
	v_cvt_pk_bf16_f32 v83, v92, v93
	v_cvt_pk_bf16_f32 v84, v96, v90
	v_cvt_pk_bf16_f32 v85, v88, v85
	flat_store_dwordx4 v[86:87], v[82:85]
	v_mov_b32_e32 v86, v78
	s_nop 0
	v_fmamk_f32 v84, v160, 0x3a000000, v223
	v_cmp_gt_f32_e32 vcc, s29, v84
	v_mul_f32_e32 v85, 0x4b800000, v84
	v_mad_i64_i32 v[82:83], s[2:3], v161, s34, v[140:141]
	v_cndmask_b32_e32 v84, v84, v85, vcc
	v_rsq_f32_e32 v84, v84
	s_nop 0
	v_mul_f32_e32 v85, 0x45800000, v84
	v_cndmask_b32_e32 v84, v84, v85, vcc
	v_mul_f32_e32 v88, 0xbfb8aa3b, v84
	v_mul_f32_e32 v85, v84, v84
	v_mul_f32_e32 v84, v78, v88
	v_exp_f32_e32 v84, v84
	s_nop 0
	v_add_f32_e32 v84, 1.0, v84
	v_rcp_f32_e32 v87, v84
	v_mov_b32_e32 v84, v74
	v_mul_f32_e32 v74, v79, v88
	v_exp_f32_e32 v74, v74
	v_pk_mul_f32 v[86:87], v[84:85], v[86:87]
	v_mov_b32_e32 v84, v75
	v_mul_f32_e32 v78, v86, v87
	v_add_f32_e32 v74, 1.0, v74
	v_rcp_f32_e32 v87, v74
	v_mov_b32_e32 v86, v79
	v_pk_mul_f32 v[74:75], v[84:85], v[86:87]
	s_nop 0
	v_mul_f32_e32 v79, v74, v75
	v_mul_f32_e32 v74, v80, v88
	v_exp_f32_e32 v74, v74
	v_mov_b32_e32 v84, v76
	v_add_f32_e32 v74, 1.0, v74
	v_rcp_f32_e32 v75, v74
	v_mov_b32_e32 v74, v80
	v_pk_mul_f32 v[74:75], v[84:85], v[74:75]
	s_nop 0
	v_mul_f32_e32 v76, v74, v75
	v_mul_f32_e32 v74, v81, v88
	v_exp_f32_e32 v74, v74
	v_mov_b32_e32 v84, v77
	v_add_f32_e32 v74, 1.0, v74
	v_rcp_f32_e32 v75, v74
	v_mov_b32_e32 v74, v81
	v_pk_mul_f32 v[74:75], v[84:85], v[74:75]
	s_nop 0
	v_mul_f32_e32 v77, v74, v75
	v_mul_f32_e32 v74, v70, v88
	v_exp_f32_e32 v74, v74
	v_mov_b32_e32 v84, v66
	v_mul_f32_e32 v66, v71, v88
	v_exp_f32_e32 v66, v66
	v_add_f32_e32 v74, 1.0, v74
	v_rcp_f32_e32 v75, v74
	v_mov_b32_e32 v74, v70
	v_add_f32_e32 v66, 1.0, v66
	v_pk_mul_f32 v[74:75], v[84:85], v[74:75]
	s_nop 0
	v_mul_f32_e32 v80, v74, v75
	v_rcp_f32_e32 v75, v66
	v_mov_b32_e32 v84, v67
	v_mov_b32_e32 v74, v71
	v_lshl_add_u64 v[70:71], v[82:83], 0, v[114:115]
	v_pk_mul_f32 v[66:67], v[84:85], v[74:75]
	v_mov_b32_e32 v84, v68
	v_mul_f32_e32 v74, v66, v67
	v_mul_f32_e32 v66, v72, v88
	v_exp_f32_e32 v66, v66
	s_nop 0
	v_add_f32_e32 v66, 1.0, v66
	v_rcp_f32_e32 v67, v66
	v_mov_b32_e32 v66, v72
	v_pk_mul_f32 v[66:67], v[84:85], v[66:67]
	s_nop 0
	v_mul_f32_e32 v72, v66, v67
	v_mul_f32_e32 v66, v73, v88
	v_exp_f32_e32 v66, v66
	v_mov_b32_e32 v84, v69
	v_add_f32_e32 v66, 1.0, v66
	v_rcp_f32_e32 v67, v66
	v_mov_b32_e32 v66, v73
	v_pk_mul_f32 v[66:67], v[84:85], v[66:67]
	s_nop 0
	v_mul_f32_e32 v69, v66, v67
	v_cvt_pk_bf16_f32 v66, v78, v79
	v_cvt_pk_bf16_f32 v67, v76, v77
	v_cvt_pk_bf16_f32 v68, v80, v74
	v_cvt_pk_bf16_f32 v69, v72, v69
	flat_store_dwordx4 v[70:71], v[66:69]
	v_mov_b32_e32 v70, v62
	s_nop 0
	v_fmamk_f32 v68, v158, 0x3a000000, v223
	v_cmp_gt_f32_e32 vcc, s29, v68
	v_mul_f32_e32 v69, 0x4b800000, v68
	v_mad_i64_i32 v[66:67], s[2:3], v159, s34, v[140:141]
	v_cndmask_b32_e32 v68, v68, v69, vcc
	v_rsq_f32_e32 v68, v68
	s_nop 0
	v_mul_f32_e32 v69, 0x45800000, v68
	v_cndmask_b32_e32 v68, v68, v69, vcc
	v_mul_f32_e32 v72, 0xbfb8aa3b, v68
	v_mul_f32_e32 v69, v68, v68
	v_mul_f32_e32 v68, v62, v72
	v_exp_f32_e32 v68, v68
	s_nop 0
	v_add_f32_e32 v68, 1.0, v68
	v_rcp_f32_e32 v71, v68
	v_mov_b32_e32 v68, v58
	v_mul_f32_e32 v58, v63, v72
	v_exp_f32_e32 v58, v58
	v_pk_mul_f32 v[70:71], v[68:69], v[70:71]
	v_mov_b32_e32 v68, v59
	v_mul_f32_e32 v62, v70, v71
	v_add_f32_e32 v58, 1.0, v58
	v_rcp_f32_e32 v71, v58
	v_mov_b32_e32 v70, v63
	v_pk_mul_f32 v[58:59], v[68:69], v[70:71]
	s_nop 0
	v_mul_f32_e32 v63, v58, v59
	v_mul_f32_e32 v58, v64, v72
	v_exp_f32_e32 v58, v58
	v_mov_b32_e32 v68, v60
; __device__ __forceinline__ unsigned pk2(float lo, float hi) { unsigned r; asm volatile("v_cvt_pk_bf16_f32 %0, %1, %2" : "=v"(r) : "v"(lo), "v"(hi)); return r; }
;     __device__ __forceinline__ void operator()(const f32x4 (&acc)[2][2][4][2], const Unit& u, int wr, int wc, int fr, int fq) const {
;     ...
;             for (int m = 0; m < 4; ++m) { bf16_t* rowp = O + (size_t)(row0 + ai * HALF + m * 16) * DFF + col0; const float rsv = rsqrtf(rs[ai][m] * (1.f / D) + EPS);
;                 const float rs2 = rsv * rsv, nrs = -1.4426950409f * rsv;
;                 float v[8];
; #pragma unroll
;                 for (int n = 0; n < 2; ++n)
; #pragma unroll
;                     for (int j = 0; j < 4; ++j) {
;                         const float g0 = acc[ai][0][m][n][j], u0 = acc[ai][1][m][n][j];
;                         v[n * 4 + j] = (g0 * u0) * (rs2 * __builtin_amdgcn_rcpf(1.0f + __builtin_amdgcn_exp2f(g0 * nrs))); }
;                 u32x4 w; w.x = pk2(v[0], v[1]); w.y = pk2(v[2], v[3]); w.z = pk2(v[4], v[5]); w.w = pk2(v[6], v[7]);
;                 *(u32x4*)rowp = w; }
	v_add_f32_e32 v58, 1.0, v58
	v_rcp_f32_e32 v59, v58
	v_mov_b32_e32 v58, v64
	v_pk_mul_f32 v[58:59], v[68:69], v[58:59]
	s_nop 0
	v_mul_f32_e32 v60, v58, v59
	v_mul_f32_e32 v58, v65, v72
	v_exp_f32_e32 v58, v58
	v_mov_b32_e32 v68, v61
	v_add_f32_e32 v58, 1.0, v58
	v_rcp_f32_e32 v59, v58
	v_mov_b32_e32 v58, v65
	v_pk_mul_f32 v[58:59], v[68:69], v[58:59]
	s_nop 0
	v_mul_f32_e32 v61, v58, v59
	v_mul_f32_e32 v58, v54, v72
	v_exp_f32_e32 v58, v58
	v_mov_b32_e32 v68, v50
	v_mul_f32_e32 v50, v55, v72
	v_exp_f32_e32 v50, v50
	v_add_f32_e32 v58, 1.0, v58
	v_rcp_f32_e32 v59, v58
	v_mov_b32_e32 v58, v54
	v_add_f32_e32 v50, 1.0, v50
	v_pk_mul_f32 v[58:59], v[68:69], v[58:59]
	s_nop 0
	v_mul_f32_e32 v64, v58, v59
	v_rcp_f32_e32 v59, v50
	v_mov_b32_e32 v68, v51
	v_mov_b32_e32 v58, v55
	v_lshl_add_u64 v[54:55], v[66:67], 0, v[114:115]
	v_pk_mul_f32 v[50:51], v[68:69], v[58:59]
	v_mov_b32_e32 v68, v52
	v_mul_f32_e32 v58, v50, v51
	v_mul_f32_e32 v50, v56, v72
	v_exp_f32_e32 v50, v50
	s_nop 0
	v_add_f32_e32 v50, 1.0, v50
	v_rcp_f32_e32 v51, v50
	v_mov_b32_e32 v50, v56
	v_pk_mul_f32 v[50:51], v[68:69], v[50:51]
	s_nop 0
	v_mul_f32_e32 v56, v50, v51
	v_mul_f32_e32 v50, v57, v72
	v_exp_f32_e32 v50, v50
	v_mov_b32_e32 v68, v53
	v_add_f32_e32 v50, 1.0, v50
	v_rcp_f32_e32 v51, v50
	v_mov_b32_e32 v50, v57
	v_pk_mul_f32 v[50:51], v[68:69], v[50:51]
	s_nop 0
	v_mul_f32_e32 v53, v50, v51
	v_cvt_pk_bf16_f32 v50, v62, v63
	v_cvt_pk_bf16_f32 v51, v60, v61
	v_cvt_pk_bf16_f32 v52, v64, v58
	v_cvt_pk_bf16_f32 v53, v56, v53
	flat_store_dwordx4 v[54:55], v[50:53]
	v_mov_b32_e32 v54, v46
	s_nop 0
	v_fmamk_f32 v52, v156, 0x3a000000, v223
	v_cmp_gt_f32_e32 vcc, s29, v52
	v_mul_f32_e32 v53, 0x4b800000, v52
	v_mad_i64_i32 v[50:51], s[2:3], v157, s34, v[140:141]
	v_cndmask_b32_e32 v52, v52, v53, vcc
	v_rsq_f32_e32 v52, v52
	s_nop 0
	v_mul_f32_e32 v53, 0x45800000, v52
	v_cndmask_b32_e32 v52, v52, v53, vcc
	v_mul_f32_e32 v56, 0xbfb8aa3b, v52
	v_mul_f32_e32 v53, v52, v52
	v_mul_f32_e32 v52, v46, v56
	v_exp_f32_e32 v52, v52
	s_nop 0
	v_add_f32_e32 v52, 1.0, v52
	v_rcp_f32_e32 v55, v52
	v_mov_b32_e32 v52, v42
	v_mul_f32_e32 v42, v47, v56
	v_exp_f32_e32 v42, v42
	v_pk_mul_f32 v[54:55], v[52:53], v[54:55]
	v_mov_b32_e32 v52, v43
	v_mul_f32_e32 v46, v54, v55
	v_add_f32_e32 v42, 1.0, v42
	v_rcp_f32_e32 v55, v42
	v_mov_b32_e32 v54, v47
	v_pk_mul_f32 v[42:43], v[52:53], v[54:55]
	s_nop 0
	v_mul_f32_e32 v47, v42, v43
	v_mul_f32_e32 v42, v48, v56
	v_exp_f32_e32 v42, v42
	v_mov_b32_e32 v52, v44
	v_add_f32_e32 v42, 1.0, v42
	v_rcp_f32_e32 v43, v42
	v_mov_b32_e32 v42, v48
	v_pk_mul_f32 v[42:43], v[52:53], v[42:43]
	s_nop 0
	v_mul_f32_e32 v44, v42, v43
	v_mul_f32_e32 v42, v49, v56
	v_exp_f32_e32 v42, v42
	v_mov_b32_e32 v52, v45
	v_add_f32_e32 v42, 1.0, v42
	v_rcp_f32_e32 v43, v42
	v_mov_b32_e32 v42, v49
	v_pk_mul_f32 v[42:43], v[52:53], v[42:43]
	s_nop 0
	v_mul_f32_e32 v45, v42, v43
	v_mul_f32_e32 v42, v38, v56
	v_exp_f32_e32 v42, v42
	v_mov_b32_e32 v52, v34
	v_mul_f32_e32 v34, v39, v56
	v_exp_f32_e32 v34, v34
	v_add_f32_e32 v42, 1.0, v42
	v_rcp_f32_e32 v43, v42
	v_mov_b32_e32 v42, v38
	v_add_f32_e32 v34, 1.0, v34
	v_pk_mul_f32 v[42:43], v[52:53], v[42:43]
	s_nop 0
	v_mul_f32_e32 v48, v42, v43
	v_rcp_f32_e32 v43, v34
	v_mov_b32_e32 v52, v35
	v_mov_b32_e32 v42, v39
	v_lshl_add_u64 v[38:39], v[50:51], 0, v[114:115]
	v_pk_mul_f32 v[34:35], v[52:53], v[42:43]
	v_mov_b32_e32 v52, v36
	v_mul_f32_e32 v42, v34, v35
	v_mul_f32_e32 v34, v40, v56
	v_exp_f32_e32 v34, v34
	s_nop 0
	v_add_f32_e32 v34, 1.0, v34
	v_rcp_f32_e32 v35, v34
	v_mov_b32_e32 v34, v40
	v_pk_mul_f32 v[34:35], v[52:53], v[34:35]
	s_nop 0
	v_mul_f32_e32 v40, v34, v35
	v_mul_f32_e32 v34, v41, v56
	v_exp_f32_e32 v34, v34
	v_mov_b32_e32 v52, v37
	v_add_f32_e32 v34, 1.0, v34
	v_rcp_f32_e32 v35, v34
	v_mov_b32_e32 v34, v41
	v_pk_mul_f32 v[34:35], v[52:53], v[34:35]
	s_nop 0
	v_mul_f32_e32 v37, v34, v35
	v_cvt_pk_bf16_f32 v34, v46, v47
	v_cvt_pk_bf16_f32 v35, v44, v45
	v_cvt_pk_bf16_f32 v36, v48, v42
	v_cvt_pk_bf16_f32 v37, v40, v37
	flat_store_dwordx4 v[38:39], v[34:37]
	v_mov_b32_e32 v38, v30
	s_nop 0
	v_fmamk_f32 v36, v154, 0x3a000000, v223
	v_cmp_gt_f32_e32 vcc, s29, v36
	v_mul_f32_e32 v37, 0x4b800000, v36
	v_mad_i64_i32 v[34:35], s[2:3], v155, s34, v[140:141]
	v_cndmask_b32_e32 v36, v36, v37, vcc
	v_rsq_f32_e32 v36, v36
	s_nop 0
	v_mul_f32_e32 v37, 0x45800000, v36
	v_cndmask_b32_e32 v36, v36, v37, vcc
	v_mul_f32_e32 v40, 0xbfb8aa3b, v36
	v_mul_f32_e32 v37, v36, v36
	v_mul_f32_e32 v36, v30, v40
	v_exp_f32_e32 v36, v36
	s_nop 0
	v_add_f32_e32 v36, 1.0, v36
	v_rcp_f32_e32 v39, v36
	v_mov_b32_e32 v36, v26
	v_mul_f32_e32 v26, v31, v40
	v_exp_f32_e32 v26, v26
	v_pk_mul_f32 v[38:39], v[36:37], v[38:39]
	v_mov_b32_e32 v36, v27
; __device__ __forceinline__ unsigned pk2(float lo, float hi) { unsigned r; asm volatile("v_cvt_pk_bf16_f32 %0, %1, %2" : "=v"(r) : "v"(lo), "v"(hi)); return r; }
; #define PG8_WAIT_V(n) asm volatile("s_waitcnt vmcnt(" #n ")" ::: "memory")
; #define PG8_BAR __builtin_amdgcn_s_barrier()
; template <class Epi, class Sched, bool ALIGN_EPI = false, bool SP2 = false>
; __device__ __forceinline__ void gemm_phase(PG8_LAS unsigned char* lds, const Gemm g, const Sched& S, const Epi& E) {
;     ...
;         if (!has_next) break;
;         if (cur.ks != -2) {
; #pragma unroll
;         for (int a = 0; a < 2; ++a)
; #pragma unroll
;             for (int b = 0; b < 2; ++b)
; #pragma unroll
;                 for (int m = 0; m < 4; ++m)
; #pragma unroll
;                     for (int n = 0; n < 2; ++n) acc[a][b][m][n] = (f32x4){0.f, 0.f, 0.f, 0.f};
;         }
;         cur = nxt; cA = nA; cB = nB; ++ui;
;         if constexpr (ALIGN_EPI) { if (wr == 1) PG8_BAR; }
;     }
;     PG8_WAIT_V(0);
;     if constexpr (!ALIGN_EPI) { if (wr == 0) PG8_BAR; }
;     PG8_BAR;
;     __device__ __forceinline__ void operator()(const f32x4 (&acc)[2][2][4][2], const Unit& u, int wr, int wc, int fr, int fq) const {
;     ...
;             for (int m = 0; m < 4; ++m) { bf16_t* rowp = O + (size_t)(row0 + ai * HALF + m * 16) * DFF + col0; const float rsv = rsqrtf(rs[ai][m] * (1.f / D) + EPS);
;                 const float rs2 = rsv * rsv, nrs = -1.4426950409f * rsv;
;                 float v[8];
; #pragma unroll
;                 for (int n = 0; n < 2; ++n)
; #pragma unroll
;                     for (int j = 0; j < 4; ++j) {
;                         const float g0 = acc[ai][0][m][n][j], u0 = acc[ai][1][m][n][j];
;                         v[n * 4 + j] = (g0 * u0) * (rs2 * __builtin_amdgcn_rcpf(1.0f + __builtin_amdgcn_exp2f(g0 * nrs))); }
;                 u32x4 w; w.x = pk2(v[0], v[1]); w.y = pk2(v[2], v[3]); w.z = pk2(v[4], v[5]); w.w = pk2(v[6], v[7]);
;                 *(u32x4*)rowp = w; }
	v_mul_f32_e32 v30, v38, v39
	v_add_f32_e32 v26, 1.0, v26
	v_rcp_f32_e32 v39, v26
	v_mov_b32_e32 v38, v31
	v_pk_mul_f32 v[26:27], v[36:37], v[38:39]
	s_nop 0
	v_mul_f32_e32 v31, v26, v27
	v_mul_f32_e32 v26, v32, v40
	v_exp_f32_e32 v26, v26
	v_mov_b32_e32 v36, v28
	v_add_f32_e32 v26, 1.0, v26
	v_rcp_f32_e32 v27, v26
	v_mov_b32_e32 v26, v32
	v_pk_mul_f32 v[26:27], v[36:37], v[26:27]
	s_nop 0
	v_mul_f32_e32 v28, v26, v27
	v_mul_f32_e32 v26, v33, v40
	v_exp_f32_e32 v26, v26
	v_mov_b32_e32 v36, v29
	v_add_f32_e32 v26, 1.0, v26
	v_rcp_f32_e32 v27, v26
	v_mov_b32_e32 v26, v33
	v_pk_mul_f32 v[26:27], v[36:37], v[26:27]
	s_nop 0
	v_mul_f32_e32 v29, v26, v27
	v_mul_f32_e32 v26, v22, v40
	v_exp_f32_e32 v26, v26
	v_mov_b32_e32 v36, v18
	v_mul_f32_e32 v18, v23, v40
	v_exp_f32_e32 v18, v18
	v_add_f32_e32 v26, 1.0, v26
	v_rcp_f32_e32 v27, v26
	v_mov_b32_e32 v26, v22
	v_add_f32_e32 v18, 1.0, v18
	v_pk_mul_f32 v[26:27], v[36:37], v[26:27]
	s_nop 0
	v_mul_f32_e32 v32, v26, v27
	v_rcp_f32_e32 v27, v18
	v_mov_b32_e32 v36, v19
	v_mov_b32_e32 v26, v23
	v_lshl_add_u64 v[22:23], v[34:35], 0, v[114:115]
	v_pk_mul_f32 v[18:19], v[36:37], v[26:27]
	v_mov_b32_e32 v36, v20
	v_mul_f32_e32 v26, v18, v19
	v_mul_f32_e32 v18, v24, v40
	v_exp_f32_e32 v18, v18
	s_nop 0
	v_add_f32_e32 v18, 1.0, v18
	v_rcp_f32_e32 v19, v18
	v_mov_b32_e32 v18, v24
	v_pk_mul_f32 v[18:19], v[36:37], v[18:19]
	s_nop 0
	v_mul_f32_e32 v24, v18, v19
	v_mul_f32_e32 v18, v25, v40
	v_exp_f32_e32 v18, v18
	v_mov_b32_e32 v36, v21
	v_add_f32_e32 v18, 1.0, v18
	v_rcp_f32_e32 v19, v18
	v_mov_b32_e32 v18, v25
	v_pk_mul_f32 v[18:19], v[36:37], v[18:19]
	s_nop 0
	v_mul_f32_e32 v21, v18, v19
	v_cvt_pk_bf16_f32 v18, v30, v31
	v_cvt_pk_bf16_f32 v19, v28, v29
	v_cvt_pk_bf16_f32 v20, v32, v26
	v_cvt_pk_bf16_f32 v21, v24, v21
	flat_store_dwordx4 v[22:23], v[18:21]
	v_mov_b32_e32 v22, v14
	s_nop 0
	v_fmamk_f32 v20, v152, 0x3a000000, v223
	v_cmp_gt_f32_e32 vcc, s29, v20
	v_mul_f32_e32 v21, 0x4b800000, v20
	v_mad_i64_i32 v[18:19], s[2:3], v153, s34, v[140:141]
	v_cndmask_b32_e32 v20, v20, v21, vcc
	v_rsq_f32_e32 v20, v20
	s_nop 0
	v_mul_f32_e32 v21, 0x45800000, v20
	v_cndmask_b32_e32 v20, v20, v21, vcc
	v_mul_f32_e32 v24, 0xbfb8aa3b, v20
	v_mul_f32_e32 v21, v20, v20
	v_mul_f32_e32 v20, v14, v24
	v_exp_f32_e32 v20, v20
	s_andn2_b64 vcc, exec, s[40:41]
	v_add_f32_e32 v20, 1.0, v20
	v_rcp_f32_e32 v23, v20
	v_mov_b32_e32 v20, v10
	v_mul_f32_e32 v10, v15, v24
	v_exp_f32_e32 v10, v10
	v_pk_mul_f32 v[22:23], v[20:21], v[22:23]
	v_mov_b32_e32 v20, v11
	v_mul_f32_e32 v14, v22, v23
	v_add_f32_e32 v10, 1.0, v10
	v_rcp_f32_e32 v23, v10
	v_mov_b32_e32 v22, v15
	v_pk_mul_f32 v[10:11], v[20:21], v[22:23]
	s_nop 0
	v_mul_f32_e32 v15, v10, v11
	v_mul_f32_e32 v10, v16, v24
	v_exp_f32_e32 v10, v10
	v_mov_b32_e32 v20, v12
	v_add_f32_e32 v10, 1.0, v10
	v_rcp_f32_e32 v11, v10
	v_mov_b32_e32 v10, v16
	v_pk_mul_f32 v[10:11], v[20:21], v[10:11]
	s_nop 0
	v_mul_f32_e32 v12, v10, v11
	v_mul_f32_e32 v10, v17, v24
	v_exp_f32_e32 v10, v10
	v_mov_b32_e32 v20, v13
	v_add_f32_e32 v10, 1.0, v10
	v_rcp_f32_e32 v11, v10
	v_mov_b32_e32 v10, v17
	v_pk_mul_f32 v[10:11], v[20:21], v[10:11]
	s_nop 0
	v_mul_f32_e32 v13, v10, v11
	v_mul_f32_e32 v10, v6, v24
	v_exp_f32_e32 v10, v10
	v_mov_b32_e32 v20, v2
	v_mul_f32_e32 v2, v7, v24
	v_exp_f32_e32 v2, v2
	v_add_f32_e32 v10, 1.0, v10
	v_rcp_f32_e32 v11, v10
	v_mov_b32_e32 v10, v6
	v_add_f32_e32 v2, 1.0, v2
	v_pk_mul_f32 v[10:11], v[20:21], v[10:11]
	s_nop 0
	v_mul_f32_e32 v16, v10, v11
	v_rcp_f32_e32 v11, v2
	v_mov_b32_e32 v20, v3
	v_mov_b32_e32 v10, v7
	v_lshl_add_u64 v[6:7], v[18:19], 0, v[114:115]
	v_pk_mul_f32 v[2:3], v[20:21], v[10:11]
	v_mov_b32_e32 v20, v4
	v_mul_f32_e32 v10, v2, v3
	v_mul_f32_e32 v2, v8, v24
	v_exp_f32_e32 v2, v2
	s_nop 0
	v_add_f32_e32 v2, 1.0, v2
	v_rcp_f32_e32 v3, v2
	v_mov_b32_e32 v2, v8
	v_pk_mul_f32 v[2:3], v[20:21], v[2:3]
	s_nop 0
	v_mul_f32_e32 v8, v2, v3
	v_mul_f32_e32 v2, v9, v24
	v_exp_f32_e32 v2, v2
	v_mov_b32_e32 v20, v5
	v_add_f32_e32 v2, 1.0, v2
	v_rcp_f32_e32 v3, v2
	v_mov_b32_e32 v2, v9
	v_pk_mul_f32 v[2:3], v[20:21], v[2:3]
	s_nop 0
	v_mul_f32_e32 v5, v2, v3
	v_cvt_pk_bf16_f32 v2, v14, v15
	v_cvt_pk_bf16_f32 v3, v12, v13
	v_cvt_pk_bf16_f32 v4, v16, v10
	v_cvt_pk_bf16_f32 v5, v8, v5
	flat_store_dwordx4 v[6:7], v[2:5]
	s_cbranch_vccnz .LBB0_1483
	s_andn2_b64 vcc, exec, s[14:15]
	s_cbranch_vccnz .LBB0_1482
	s_barrier
	s_branch .LBB0_1482
	s_nop 0
	s_nop 0
	s_nop 0
.LBB0_1493:
	s_waitcnt vmcnt(0)
	v_readlane_b32 s24, v250, 16
	v_readlane_b32 s36, v250, 18
	v_readlane_b32 s42, v250, 20
	v_readlane_b32 s40, v250, 22
	v_readlane_b32 s25, v250, 17
	v_readlane_b32 s37, v250, 19
	v_readlane_b32 s43, v250, 21
	v_readlane_b32 s41, v250, 23
	s_barrier
